# embedded LDS staging writes moved to before MFMA 16 (no in-half load wait)
# speedup vs baseline: 1.0052x; 1.0023x over previous
.Lp1a_end:
	s_waitcnt lgkmcnt(11)
	v_mfma_f32_32x32x16_bf16 v[82:97], v[164:167], v[126:129], v[82:97]
	v_exp_f32_e32 v62, v62
	v_add_f32_e32 v200, v200, v54
	v_exp_f32_e32 v63, v63
	v_add_f32_e32 v201, v201, v55
	v_exp_f32_e32 v64, v64
	s_waitcnt lgkmcnt(10)
	v_mfma_f32_32x32x16_bf16 v[98:113], v[168:171], v[126:129], v[98:113]
	ds_read2_b64 v[164:167], v242 offset0:4 offset1:6
	ds_read2_b64 v[168:171], v163 offset0:36 offset1:38
	v_add_f32_e32 v200, v200, v56
	v_exp_f32_e32 v65, v65
	v_add_f32_e32 v201, v201, v57
	v_cvt_pk_bf16_f32 v228, v58, v59
	v_cvt_pk_bf16_f32 v229, v60, v61
	s_waitcnt lgkmcnt(11)
	v_mfma_f32_32x32x16_bf16 v[18:33], v[238:241], v[224:227], v[18:33]
	v_cvt_pk_bf16_f32 v230, v62, v63
	v_cvt_pk_bf16_f32 v231, v64, v65
	v_exp_f32_e32 v66, v66
	v_add_f32_e32 v200, v200, v58
	v_exp_f32_e32 v67, v67
	v_add_f32_e32 v201, v201, v59
	s_waitcnt lgkmcnt(10)
	v_mfma_f32_32x32x16_bf16 v[34:49], v[234:237], v[224:227], v[34:49]
	v_exp_f32_e32 v68, v68
	v_add_f32_e32 v200, v200, v60
	v_exp_f32_e32 v69, v69
	v_add_f32_e32 v201, v201, v61
	v_exp_f32_e32 v70, v70
	s_waitcnt lgkmcnt(9)
	v_mfma_f32_32x32x16_bf16 v[82:97], v[172:175], v[134:137], v[82:97]
	v_add_f32_e32 v200, v200, v62
	v_exp_f32_e32 v71, v71
	v_add_f32_e32 v201, v201, v63
	v_exp_f32_e32 v72, v72
	v_add_f32_e32 v200, v200, v64
	s_waitcnt lgkmcnt(8)
	v_mfma_f32_32x32x16_bf16 v[98:113], v[176:179], v[134:137], v[98:113]
	ds_read2_b64 v[172:175], v242 offset0:8 offset1:10
	ds_read2_b64 v[176:179], v163 offset0:40 offset1:42
	v_exp_f32_e32 v73, v73
	v_add_f32_e32 v201, v201, v65
	v_cvt_pk_bf16_f32 v224, v66, v67
	v_cvt_pk_bf16_f32 v225, v68, v69
	v_cvt_pk_bf16_f32 v226, v70, v71
	s_waitcnt lgkmcnt(3)
	v_mfma_f32_32x32x16_bf16 v[18:33], v[164:167], v[228:231], v[18:33]
	v_cvt_pk_bf16_f32 v227, v72, v73
	v_exp_f32_e32 v74, v74
	v_add_f32_e32 v200, v200, v66
	v_exp_f32_e32 v75, v75
	v_add_f32_e32 v201, v201, v67
	s_waitcnt lgkmcnt(2)
	v_mfma_f32_32x32x16_bf16 v[34:49], v[168:171], v[228:231], v[34:49]
	v_exp_f32_e32 v76, v76
	v_add_f32_e32 v200, v200, v68
	v_exp_f32_e32 v77, v77
	v_add_f32_e32 v201, v201, v69
	v_exp_f32_e32 v78, v78
	s_waitcnt lgkmcnt(9)
	v_mfma_f32_32x32x16_bf16 v[82:97], v[180:183], v[138:141], v[82:97]
	v_add_f32_e32 v200, v200, v70
	v_exp_f32_e32 v79, v79
	v_add_f32_e32 v201, v201, v71
	v_exp_f32_e32 v80, v80
	v_add_f32_e32 v200, v200, v72
	s_waitcnt lgkmcnt(8)
	v_mfma_f32_32x32x16_bf16 v[98:113], v[184:187], v[138:141], v[98:113]
	ds_read2_b64 v[180:183], v242 offset0:12 offset1:14
	ds_read2_b64 v[184:187], v163 offset0:44 offset1:46
	v_exp_f32_e32 v81, v81
	v_add_f32_e32 v201, v201, v73
	v_cvt_pk_bf16_f32 v228, v74, v75
	v_cvt_pk_bf16_f32 v229, v76, v77
	v_cvt_pk_bf16_f32 v230, v78, v79
	s_waitcnt lgkmcnt(3)
	v_mfma_f32_32x32x16_bf16 v[18:33], v[172:175], v[224:227], v[18:33]
	v_cvt_pk_bf16_f32 v231, v80, v81
	v_add_f32_e32 v200, v200, v74
	v_add_f32_e32 v201, v201, v75
	v_add_f32_e32 v200, v200, v76
	v_add_f32_e32 v201, v201, v77
	v_add_f32_e32 v200, v200, v78
	v_add_f32_e32 v201, v201, v79
	v_add_f32_e32 v200, v200, v80
	s_waitcnt lgkmcnt(2)
	v_mfma_f32_32x32x16_bf16 v[34:49], v[176:179], v[224:227], v[34:49]
	v_add_f32_e32 v201, v201, v81
	v_add_f32_e32 v200, v200, v201
	v_add_f32_e32 v162, v162, v200
	s_waitcnt lgkmcnt(9)
	v_mfma_f32_32x32x16_bf16 v[82:97], v[188:191], v[142:145], v[82:97]
	s_waitcnt lgkmcnt(0)
	v_cndmask_b32_e64 v0, 0, 1, s[44:45]
	v_cmp_ne_u32_e64 s[42:43], 1, v0
	s_andn2_b64 vcc, exec, s[44:45]
	s_cbranch_vccnz .Lt1a_mid
	s_and_b32 s44, s53, 2
	s_mulk_i32 s44, 0x3400
	s_add_i32 s62, s44, 0
	v_add_u32_e32 v0, s62, v151
	ds_write_b128 v0, v[118:121]
	s_and_saveexec_b64 s[44:45], s[40:41]
	v_add_u32_e32 v0, s62, v159
	ds_write_b128 v0, v[6:9]
	s_or_b64 exec, exec, s[44:45]

.Lp2a_end:
	s_waitcnt lgkmcnt(11)
	v_mfma_f32_32x32x16_bf16 v[50:65], v[164:167], v[126:129], v[50:65]
	v_exp_f32_e32 v94, v94
	v_add_f32_e32 v200, v200, v86
	v_exp_f32_e32 v95, v95
	v_add_f32_e32 v201, v201, v87
	v_exp_f32_e32 v96, v96
	s_waitcnt lgkmcnt(10)
	v_mfma_f32_32x32x16_bf16 v[66:81], v[168:171], v[126:129], v[66:81]
	ds_read2_b64 v[164:167], v242 offset0:4 offset1:6
	ds_read2_b64 v[168:171], v163 offset0:36 offset1:38
	v_add_f32_e32 v200, v200, v88
	v_exp_f32_e32 v97, v97
	v_add_f32_e32 v201, v201, v89
	v_cvt_pk_bf16_f32 v228, v90, v91
	v_cvt_pk_bf16_f32 v229, v92, v93
	s_waitcnt lgkmcnt(11)
	v_mfma_f32_32x32x16_bf16 v[18:33], v[238:241], v[224:227], v[18:33]
	v_cvt_pk_bf16_f32 v230, v94, v95
	v_cvt_pk_bf16_f32 v231, v96, v97
	v_exp_f32_e32 v98, v98
	v_add_f32_e32 v200, v200, v90
	v_exp_f32_e32 v99, v99
	v_add_f32_e32 v201, v201, v91
	s_waitcnt lgkmcnt(10)
	v_mfma_f32_32x32x16_bf16 v[34:49], v[234:237], v[224:227], v[34:49]
	v_exp_f32_e32 v100, v100
	v_add_f32_e32 v200, v200, v92
	v_exp_f32_e32 v101, v101
	v_add_f32_e32 v201, v201, v93
	v_exp_f32_e32 v102, v102
	s_waitcnt lgkmcnt(9)
	v_mfma_f32_32x32x16_bf16 v[50:65], v[172:175], v[134:137], v[50:65]
	v_add_f32_e32 v200, v200, v94
	v_exp_f32_e32 v103, v103
	v_add_f32_e32 v201, v201, v95
	v_exp_f32_e32 v104, v104
	v_add_f32_e32 v200, v200, v96
	s_waitcnt lgkmcnt(8)
	v_mfma_f32_32x32x16_bf16 v[66:81], v[176:179], v[134:137], v[66:81]
	ds_read2_b64 v[172:175], v242 offset0:8 offset1:10
	ds_read2_b64 v[176:179], v163 offset0:40 offset1:42
	v_exp_f32_e32 v105, v105
	v_add_f32_e32 v201, v201, v97
	v_cvt_pk_bf16_f32 v224, v98, v99
	v_cvt_pk_bf16_f32 v225, v100, v101
	v_cvt_pk_bf16_f32 v226, v102, v103
	s_waitcnt lgkmcnt(3)
	v_mfma_f32_32x32x16_bf16 v[18:33], v[164:167], v[228:231], v[18:33]
	v_cvt_pk_bf16_f32 v227, v104, v105
	v_exp_f32_e32 v106, v106
	v_add_f32_e32 v200, v200, v98
	v_exp_f32_e32 v107, v107
	v_add_f32_e32 v201, v201, v99
	s_waitcnt lgkmcnt(2)
	v_mfma_f32_32x32x16_bf16 v[34:49], v[168:171], v[228:231], v[34:49]
	v_exp_f32_e32 v108, v108
	v_add_f32_e32 v200, v200, v100
	v_exp_f32_e32 v109, v109
	v_add_f32_e32 v201, v201, v101
	v_exp_f32_e32 v110, v110
	s_waitcnt lgkmcnt(9)
	v_mfma_f32_32x32x16_bf16 v[50:65], v[180:183], v[138:141], v[50:65]
	v_add_f32_e32 v200, v200, v102
	v_exp_f32_e32 v111, v111
	v_add_f32_e32 v201, v201, v103
	v_exp_f32_e32 v112, v112
	v_add_f32_e32 v200, v200, v104
	s_waitcnt lgkmcnt(8)
	v_mfma_f32_32x32x16_bf16 v[66:81], v[184:187], v[138:141], v[66:81]
	ds_read2_b64 v[180:183], v242 offset0:12 offset1:14
	ds_read2_b64 v[184:187], v163 offset0:44 offset1:46
	v_exp_f32_e32 v113, v113
	v_add_f32_e32 v201, v201, v105
	v_cvt_pk_bf16_f32 v228, v106, v107
	v_cvt_pk_bf16_f32 v229, v108, v109
	v_cvt_pk_bf16_f32 v230, v110, v111
	s_waitcnt lgkmcnt(3)
	v_mfma_f32_32x32x16_bf16 v[18:33], v[172:175], v[224:227], v[18:33]
	v_cvt_pk_bf16_f32 v231, v112, v113
	v_add_f32_e32 v200, v200, v106
	v_add_f32_e32 v201, v201, v107
	v_add_f32_e32 v200, v200, v108
	v_add_f32_e32 v201, v201, v109
	v_add_f32_e32 v200, v200, v110
	v_add_f32_e32 v201, v201, v111
	v_add_f32_e32 v200, v200, v112
	s_waitcnt lgkmcnt(2)
	v_mfma_f32_32x32x16_bf16 v[34:49], v[176:179], v[224:227], v[34:49]
	v_add_f32_e32 v201, v201, v113
	v_add_f32_e32 v200, v200, v201
	v_add_f32_e32 v162, v162, v200
	s_waitcnt lgkmcnt(9)
	v_mfma_f32_32x32x16_bf16 v[50:65], v[188:191], v[142:145], v[50:65]
	s_waitcnt lgkmcnt(0)
	s_mul_i32 s58, s25, 0x2200
	s_and_b64 vcc, exec, s[44:45]
	s_cbranch_vccnz .Lt2a_mid
	s_and_b32 s44, s60, 3
	s_mulk_i32 s44, 0x3400
	s_add_i32 s52, s44, 0
	v_add_u32_e32 v0, s52, v151
	ds_write_b128 v0, v[2:5]
	s_and_saveexec_b64 s[44:45], s[40:41]
	v_add_u32_e32 v0, s52, v159
	ds_write_b128 v0, v[10:13]
	s_or_b64 exec, exec, s[44:45]
